# MoBA: softmax row-sum chain deferred into the next tile's QK MFMA burst (idle VALU slots), bit-identical order; P7/P9 epilogue trims
# speedup vs baseline: 1.0015x; 1.0015x over previous
.LBB0_906:
	s_lshl_b64 s[4:5], s[0:1], 18
	v_readlane_b32 s1, v240, 22
	s_add_u32 s2, s1, s4
	v_readlane_b32 s1, v240, 26
	s_addc_u32 s3, s1, s5
	v_readlane_b32 s1, v240, 34
	s_add_u32 s12, s1, s4
	v_readlane_b32 s1, v240, 35
	s_addc_u32 s13, s1, s5
	v_lshl_add_u64 v[0:1], s[2:3], 0, v[152:153]
	s_movk_i32 s1, 0x2000
	v_lshl_add_u64 v[2:3], s[12:13], 0, v[152:153]
	global_load_dwordx4 v[96:99], v[0:1], off
	global_load_dwordx4 v[100:103], v[2:3], off
	v_add_co_u32_e32 v0, vcc, s1, v0
	v_mov_b32_e32 v14, v151
	s_nop 0
	v_addc_co_u32_e32 v1, vcc, 0, v1, vcc
	v_add_co_u32_e32 v2, vcc, s1, v2
	v_mov_b32_e32 v15, v151
	s_nop 0
	v_addc_co_u32_e32 v3, vcc, 0, v3, vcc
	global_load_dwordx4 v[104:107], v[0:1], off
	global_load_dwordx4 v[108:111], v[2:3], off
	s_lshl_b32 s1, s93, 2
	v_mov_b32_e32 v0, v151
	v_mov_b32_e32 v1, v151
	v_mov_b32_e32 v2, v151
	v_mov_b32_e32 v3, v151
	v_mov_b32_e32 v4, v151
	v_mov_b32_e32 v5, v151
	v_mov_b32_e32 v6, v151
	v_mov_b32_e32 v7, v151
	v_mov_b32_e32 v8, v151
	v_mov_b32_e32 v9, v151
	v_mov_b32_e32 v10, v151
	v_mov_b32_e32 v11, v151
	v_mov_b32_e32 v12, v151
	v_mov_b32_e32 v13, v151
	v_mov_b64_e32 v[30:31], v[14:15]
	v_mov_b64_e32 v[46:47], v[14:15]
	s_or_b32 s2, s1, 3
	s_mov_b32 s3, 0
	v_lshl_add_u64 v[130:131], v[142:143], 0, s[4:5]
	v_mov_b32_e32 v147, 0
	v_mov_b32_e32 v148, 0
	v_mov_b64_e32 v[28:29], v[12:13]
	v_mov_b64_e32 v[26:27], v[10:11]
	v_mov_b64_e32 v[24:25], v[8:9]
	v_mov_b64_e32 v[22:23], v[6:7]
	v_mov_b64_e32 v[20:21], v[4:5]
	v_mov_b64_e32 v[18:19], v[2:3]
	v_mov_b64_e32 v[16:17], v[0:1]
	v_mov_b64_e32 v[44:45], v[12:13]
	v_mov_b64_e32 v[42:43], v[10:11]
	v_mov_b64_e32 v[40:41], v[8:9]
	v_mov_b64_e32 v[38:39], v[6:7]
	v_mov_b64_e32 v[36:37], v[4:5]
	v_mov_b64_e32 v[34:35], v[2:3]
	v_mov_b64_e32 v[32:33], v[0:1]
	s_mov_b32 s13, 0
	s_mov_b64 s[100:101], 0

.LBB0_913:
	v_cmp_lt_i32_e32 vcc, -1, v213
	s_and_b64 s[4:5], s[14:15], vcc
	v_cndmask_b32_e64 v48, 0, 1, s[4:5]
	v_cmp_ne_u32_e32 vcc, 0, v48
	s_cbranch_vccz .LBB0_921
	v_add_u32_e32 v124, v159, v132
	v_cmp_lt_i32_e32 vcc, 62, v213
	s_xor_b64 s[52:53], s[4:5], -1
	ds_read_b128 v[112:115], v124
	ds_read_b128 v[116:119], v124 offset:32
	s_or_b64 s[16:17], vcc, s[52:53]
	v_cndmask_b32_e64 v48, 0, 1, s[16:17]
	s_and_b64 s[14:15], s[14:15], vcc
	v_cmp_ne_u32_e32 vcc, 0, v48
	s_cmp_lg_u64 vcc, exec
	s_cselect_b64 s[16:17], -1, 0
	s_or_b64 s[14:15], s[14:15], s[16:17]
	v_cndmask_b32_e64 v48, v210, 0, s[14:15]
	v_pk_add_f32 v[62:63], v[46:47], v[48:49] op_sel_hi:[1,0]
	v_pk_add_f32 v[60:61], v[44:45], v[48:49] op_sel_hi:[1,0]
	v_pk_add_f32 v[58:59], v[42:43], v[48:49] op_sel_hi:[1,0]
	v_pk_add_f32 v[56:57], v[40:41], v[48:49] op_sel_hi:[1,0]
	v_pk_add_f32 v[54:55], v[38:39], v[48:49] op_sel_hi:[1,0]
	v_pk_add_f32 v[52:53], v[36:37], v[48:49] op_sel_hi:[1,0]
	v_pk_add_f32 v[50:51], v[34:35], v[48:49] op_sel_hi:[1,0]
	v_pk_add_f32 v[48:49], v[32:33], v[48:49] op_sel_hi:[1,0]
	s_cmp_eq_u64 vcc, exec
	s_waitcnt lgkmcnt(1)
	v_mfma_f32_32x32x16_bf16 v[64:79], v[112:115], v[80:83], v[48:63]
	v_add_f32_e32 v249, v216, v214
	v_add_f32_e32 v250, v217, v215
	v_add_f32_e32 v249, v218, v249
	v_add_f32_e32 v250, v219, v250
	ds_read_b128 v[112:115], v124 offset:4608
	ds_read_b128 v[120:123], v124 offset:4640
	s_waitcnt lgkmcnt(1)
	v_mfma_f32_32x32x16_bf16 v[48:63], v[112:115], v[80:83], v[48:63]
	v_add_f32_e32 v249, v220, v249
	v_add_f32_e32 v250, v221, v250
	v_add_f32_e32 v249, v224, v249
	v_add_f32_e32 v250, v225, v250
	v_mfma_f32_32x32x16_bf16 v[64:79], v[116:119], v[84:87], v[64:79]
	v_add_f32_e32 v249, v234, v249
	v_add_f32_e32 v250, v235, v250
	v_add_f32_e32 v249, v226, v249
	v_add_f32_e32 v250, v227, v250
	ds_read_b128 v[112:115], v124 offset:64
	ds_read_b128 v[116:119], v124 offset:96
	s_waitcnt lgkmcnt(2)
	v_mfma_f32_32x32x16_bf16 v[48:63], v[120:123], v[84:87], v[48:63]
	v_add_f32_e32 v249, v236, v249
	v_add_f32_e32 v250, v237, v250
	v_add_f32_e32 v249, v228, v249
	v_add_f32_e32 v250, v229, v250
	s_waitcnt lgkmcnt(1)
	v_mfma_f32_32x32x16_bf16 v[64:79], v[112:115], v[88:91], v[64:79]
	v_add_f32_e32 v249, v238, v249
	v_add_f32_e32 v250, v239, v250
	v_add_f32_e32 v249, v230, v249
	v_add_f32_e32 v250, v231, v250
	ds_read_b128 v[112:115], v124 offset:4672
	ds_read_b128 v[252:255], v124 offset:4704
	s_waitcnt lgkmcnt(1)
	v_mfma_f32_32x32x16_bf16 v[48:63], v[112:115], v[88:91], v[48:63]
	v_add_f32_e32 v249, v241, v249
	v_add_f32_e32 v250, v242, v250
	v_add_f32_e32 v249, v232, v249
	v_add_f32_e32 v250, v233, v250
	v_mfma_f32_32x32x16_bf16 v[64:79], v[116:119], v[92:95], v[64:79]
	v_add_f32_e32 v249, v243, v249
	v_add_f32_e32 v250, v244, v250
	v_add_f32_e32 v249, v247, v249
	v_add_f32_e32 v250, v248, v250
	ds_read_b64_tr_b16 v[120:121], v160 offset:18432
	ds_read_b64_tr_b16 v[122:123], v160 offset:19968
	ds_read_b64_tr_b16 v[114:115], v160 offset:20032
	ds_read_b64_tr_b16 v[112:113], v160 offset:18496
	ds_read_b64_tr_b16 v[124:125], v160 offset:21504
	ds_read_b64_tr_b16 v[126:127], v160 offset:23040
	ds_read_b64_tr_b16 v[118:119], v160 offset:23104
	ds_read_b64_tr_b16 v[116:117], v160 offset:21568
	s_waitcnt lgkmcnt(8)
	v_mfma_f32_32x32x16_bf16 v[48:63], v[252:255], v[92:95], v[48:63]
	v_add_f32_e32 v249, v245, v249
	v_add_f32_e32 v250, v246, v250
	v_add_f32_e32 v249, v249, v250
	v_cndmask_b32_e64 v249, 0, v249, s[100:101]
	v_add_f32_e32 v147, v147, v249
	s_mov_b64 s[100:101], 0
	s_cbranch_scc1 .LBB0_918
	v_cmp_le_u32_e64 s[14:15], v161, v213
	v_cmp_le_u32_e64 s[16:17], v162, v213
	v_cmp_le_u32_e64 s[18:19], v164, v213
	v_cmp_le_u32_e64 s[20:21], v166, v213
	v_cmp_le_u32_e64 s[22:23], v168, v213
	v_cmp_le_u32_e64 s[24:25], v170, v213
	v_cmp_le_u32_e64 s[26:27], v172, v213
	v_cmp_le_u32_e64 s[28:29], v174, v213
	v_cmp_le_u32_e64 s[30:31], v176, v213
	v_cmp_le_u32_e64 s[34:35], v178, v213
	v_cmp_le_u32_e64 s[36:37], v180, v213
	v_cmp_le_u32_e64 s[38:39], v182, v213
	v_cmp_le_u32_e64 s[40:41], v184, v213
	v_cmp_le_u32_e64 s[42:43], v186, v213
	v_cmp_le_u32_e64 s[44:45], v189, v213
	s_and_b64 s[14:15], s[4:5], s[14:15]
	s_and_b64 s[16:17], s[4:5], s[16:17]
	s_and_b64 s[18:19], s[4:5], s[18:19]
	s_and_b64 s[20:21], s[4:5], s[20:21]
	s_and_b64 s[22:23], s[4:5], s[22:23]
	s_and_b64 s[24:25], s[4:5], s[24:25]
	s_and_b64 s[26:27], s[4:5], s[26:27]
	s_and_b64 s[28:29], s[4:5], s[28:29]
	s_and_b64 s[30:31], s[4:5], s[30:31]
	s_and_b64 s[34:35], s[4:5], s[34:35]
	s_and_b64 s[36:37], s[4:5], s[36:37]
	s_and_b64 s[38:39], s[4:5], s[38:39]
	s_and_b64 s[40:41], s[4:5], s[40:41]
	s_and_b64 s[42:43], s[4:5], s[42:43]
	s_and_b64 s[44:45], s[4:5], s[44:45]
	v_cmp_gt_u32_e64 s[46:47], v191, v213
	v_cmp_le_u32_e32 vcc, v138, v213
	v_cndmask_b32_e64 v48, v210, v48, s[14:15]
	v_cmp_lt_u32_e64 s[14:15], v138, v213
	v_cndmask_b32_e64 v49, v210, v49, s[16:17]
	v_cmp_le_u32_e64 s[16:17], v163, v213
	v_cndmask_b32_e64 v50, v210, v50, s[18:19]
	v_cmp_le_u32_e64 s[18:19], v165, v213
	v_cndmask_b32_e64 v51, v210, v51, s[20:21]
	v_cmp_le_u32_e64 s[20:21], v167, v213
	v_cndmask_b32_e64 v52, v210, v52, s[22:23]
	v_cmp_le_u32_e64 s[22:23], v169, v213
	v_cndmask_b32_e64 v53, v210, v53, s[24:25]
	v_cmp_le_u32_e64 s[24:25], v171, v213
	v_cndmask_b32_e64 v54, v210, v54, s[26:27]
	v_cmp_le_u32_e64 s[26:27], v173, v213
	v_cndmask_b32_e64 v55, v210, v55, s[28:29]
	v_cmp_le_u32_e64 s[28:29], v175, v213
	v_cndmask_b32_e64 v56, v210, v56, s[30:31]
	v_cmp_le_u32_e64 s[30:31], v177, v213
	v_cndmask_b32_e64 v57, v210, v57, s[34:35]
	v_cmp_le_u32_e64 s[34:35], v179, v213
	v_cndmask_b32_e64 v58, v210, v58, s[36:37]
	v_cmp_le_u32_e64 s[36:37], v181, v213
	v_cndmask_b32_e64 v59, v210, v59, s[38:39]
	v_cmp_le_u32_e64 s[38:39], v183, v213
	v_cndmask_b32_e64 v60, v210, v60, s[40:41]
	v_cmp_le_u32_e64 s[40:41], v185, v213
	v_cndmask_b32_e64 v61, v210, v61, s[42:43]
	v_cmp_le_u32_e64 s[42:43], v187, v213
	v_cndmask_b32_e64 v62, v210, v62, s[44:45]
	v_cmp_le_u32_e64 s[44:45], v190, v213
	s_or_b64 s[52:53], s[52:53], s[46:47]
	s_and_saveexec_b64 s[46:47], s[52:53]
	v_mov_b32_e32 v63, s33
	s_or_b64 exec, exec, s[46:47]
	s_and_b64 vcc, s[4:5], vcc
	v_cndmask_b32_e32 v64, v210, v64, vcc
	s_and_b64 vcc, s[4:5], s[14:15]
	v_cndmask_b32_e32 v65, v210, v65, vcc
	s_and_b64 vcc, s[4:5], s[16:17]
	v_cndmask_b32_e32 v66, v210, v66, vcc
	s_and_b64 vcc, s[4:5], s[18:19]
	v_cndmask_b32_e32 v67, v210, v67, vcc
	s_and_b64 vcc, s[4:5], s[20:21]
	v_cndmask_b32_e32 v68, v210, v68, vcc
	s_and_b64 vcc, s[4:5], s[22:23]
	v_cndmask_b32_e32 v69, v210, v69, vcc
	s_and_b64 vcc, s[4:5], s[24:25]
	v_cndmask_b32_e32 v70, v210, v70, vcc
	s_and_b64 vcc, s[4:5], s[26:27]
	v_cndmask_b32_e32 v71, v210, v71, vcc
	s_and_b64 vcc, s[4:5], s[28:29]
	v_cndmask_b32_e32 v72, v210, v72, vcc
	s_and_b64 vcc, s[4:5], s[30:31]
	v_cndmask_b32_e32 v73, v210, v73, vcc
	s_and_b64 vcc, s[4:5], s[34:35]
	v_cndmask_b32_e32 v74, v210, v74, vcc
	s_and_b64 vcc, s[4:5], s[36:37]
	v_cndmask_b32_e32 v75, v210, v75, vcc
	s_and_b64 vcc, s[4:5], s[38:39]
	v_cndmask_b32_e32 v76, v210, v76, vcc
	s_and_b64 vcc, s[4:5], s[40:41]
	v_cndmask_b32_e32 v77, v210, v77, vcc
	s_and_b64 vcc, s[4:5], s[42:43]
	v_cndmask_b32_e32 v78, v210, v78, vcc
	s_and_b64 vcc, s[4:5], s[44:45]
	v_cndmask_b32_e32 v79, v210, v79, vcc

.LBB0_920:
	v_exp_f32_e32 v215, v64
	v_exp_f32_e32 v214, v48
	v_exp_f32_e32 v217, v65
	v_exp_f32_e32 v216, v49
	v_exp_f32_e32 v219, v66
	v_exp_f32_e32 v218, v50
	v_exp_f32_e32 v221, v67
	v_exp_f32_e32 v225, v68
	v_exp_f32_e32 v235, v69
	v_exp_f32_e32 v227, v70
	v_exp_f32_e32 v237, v71
	v_exp_f32_e32 v220, v51
	v_cvt_pk_bf16_f32 v50, v225, v235
	v_cvt_pk_bf16_f32 v48, v215, v217
	v_cvt_pk_bf16_f32 v49, v219, v221
	v_cvt_pk_bf16_f32 v51, v227, v237
	v_exp_f32_e32 v229, v72
	v_exp_f32_e32 v239, v73
	s_waitcnt lgkmcnt(6)
	v_mfma_f32_32x32x16_bf16 v[0:15], v[120:123], v[48:51], v[0:15]
	v_exp_f32_e32 v231, v74
	v_exp_f32_e32 v242, v75
	v_exp_f32_e32 v233, v76
	v_exp_f32_e32 v244, v77
	v_exp_f32_e32 v248, v78
	v_exp_f32_e32 v246, v79
	v_cvt_pk_bf16_f32 v64, v229, v239
	s_waitcnt lgkmcnt(4)
	v_mfma_f32_32x32x16_bf16 v[16:31], v[112:115], v[48:51], v[16:31]
	v_cvt_pk_bf16_f32 v65, v231, v242
	v_cvt_pk_bf16_f32 v66, v233, v244
	v_cvt_pk_bf16_f32 v67, v248, v246
	v_exp_f32_e32 v224, v52
	v_exp_f32_e32 v234, v53
	v_exp_f32_e32 v226, v54
	v_exp_f32_e32 v236, v55
	s_waitcnt lgkmcnt(2)
	v_mfma_f32_32x32x16_bf16 v[0:15], v[124:127], v[64:67], v[0:15]
	ds_read_b64_tr_b16 v[48:49], v160 offset:24576
	ds_read_b64_tr_b16 v[50:51], v160 offset:26112
	v_exp_f32_e32 v228, v56
	v_exp_f32_e32 v238, v57
	v_exp_f32_e32 v230, v58
	v_exp_f32_e32 v241, v59
	ds_read_b64_tr_b16 v[52:53], v160 offset:27648
	ds_read_b64_tr_b16 v[54:55], v160 offset:29184
	ds_read_b64_tr_b16 v[58:59], v160 offset:26176
	ds_read_b64_tr_b16 v[56:57], v160 offset:24640
	v_exp_f32_e32 v232, v60
	s_waitcnt lgkmcnt(6)
	v_mfma_f32_32x32x16_bf16 v[16:31], v[116:119], v[64:67], v[16:31]
	v_cvt_pk_bf16_f32 v64, v214, v216
	v_cvt_pk_bf16_f32 v65, v218, v220
	v_cvt_pk_bf16_f32 v66, v224, v234
	v_cvt_pk_bf16_f32 v67, v226, v236
	v_exp_f32_e32 v243, v61
	v_exp_f32_e32 v247, v62
	v_exp_f32_e32 v245, v63
	s_waitcnt lgkmcnt(4)
	v_mfma_f32_32x32x16_bf16 v[0:15], v[48:51], v[64:67], v[0:15]
	v_cvt_pk_bf16_f32 v60, v228, v238
	v_cvt_pk_bf16_f32 v61, v230, v241
	v_cvt_pk_bf16_f32 v62, v232, v243
	v_cvt_pk_bf16_f32 v63, v247, v245
	ds_read_b64_tr_b16 v[50:51], v160 offset:29248
	ds_read_b64_tr_b16 v[48:49], v160 offset:27712
	s_waitcnt lgkmcnt(2)
	v_mfma_f32_32x32x16_bf16 v[16:31], v[56:59], v[64:67], v[16:31]
	v_mfma_f32_32x32x16_bf16 v[0:15], v[52:55], v[60:63], v[0:15]
	s_waitcnt lgkmcnt(0)
	v_mfma_f32_32x32x16_bf16 v[16:31], v[48:51], v[60:63], v[16:31]
	s_mov_b64 s[100:101], -1

.LBB0_928:
	v_cmp_lt_i32_e32 vcc, -1, v149
	s_and_b64 s[4:5], s[14:15], vcc
	v_cndmask_b32_e64 v48, 0, 1, s[4:5]
	v_cmp_ne_u32_e32 vcc, 0, v48
	s_cbranch_vccz .LBB0_936
	v_add_u32_e32 v124, v159, v132
	v_cmp_lt_i32_e32 vcc, 62, v149
	s_xor_b64 s[50:51], s[4:5], -1
	ds_read_b128 v[112:115], v124 offset:9216
	ds_read_b128 v[116:119], v124 offset:9248
	s_or_b64 s[16:17], vcc, s[50:51]
	v_cndmask_b32_e64 v48, 0, 1, s[16:17]
	s_and_b64 s[14:15], s[14:15], vcc
	v_cmp_ne_u32_e32 vcc, 0, v48
	s_cmp_lg_u64 vcc, exec
	s_cselect_b64 s[16:17], -1, 0
	s_or_b64 s[14:15], s[14:15], s[16:17]
	v_cndmask_b32_e64 v48, v210, 0, s[14:15]
	v_pk_add_f32 v[62:63], v[46:47], v[48:49] op_sel_hi:[1,0]
	v_pk_add_f32 v[60:61], v[44:45], v[48:49] op_sel_hi:[1,0]
	v_pk_add_f32 v[58:59], v[42:43], v[48:49] op_sel_hi:[1,0]
	v_pk_add_f32 v[56:57], v[40:41], v[48:49] op_sel_hi:[1,0]
	v_pk_add_f32 v[54:55], v[38:39], v[48:49] op_sel_hi:[1,0]
	v_pk_add_f32 v[52:53], v[36:37], v[48:49] op_sel_hi:[1,0]
	v_pk_add_f32 v[50:51], v[34:35], v[48:49] op_sel_hi:[1,0]
	v_pk_add_f32 v[48:49], v[32:33], v[48:49] op_sel_hi:[1,0]
	s_cmp_eq_u64 vcc, exec
	s_waitcnt lgkmcnt(1)
	v_mfma_f32_32x32x16_bf16 v[64:79], v[112:115], v[80:83], v[48:63]
	v_add_f32_e32 v249, v216, v214
	v_add_f32_e32 v250, v217, v215
	v_add_f32_e32 v249, v218, v249
	v_add_f32_e32 v250, v219, v250
	ds_read_b128 v[112:115], v124 offset:13824
	ds_read_b128 v[120:123], v124 offset:13856
	s_waitcnt lgkmcnt(1)
	v_mfma_f32_32x32x16_bf16 v[48:63], v[112:115], v[80:83], v[48:63]
	v_add_f32_e32 v249, v220, v249
	v_add_f32_e32 v250, v221, v250
	v_add_f32_e32 v249, v224, v249
	v_add_f32_e32 v250, v225, v250
	v_mfma_f32_32x32x16_bf16 v[64:79], v[116:119], v[84:87], v[64:79]
	v_add_f32_e32 v249, v234, v249
	v_add_f32_e32 v250, v235, v250
	v_add_f32_e32 v249, v226, v249
	v_add_f32_e32 v250, v227, v250
	ds_read_b128 v[112:115], v124 offset:9280
	ds_read_b128 v[116:119], v124 offset:9312
	s_waitcnt lgkmcnt(2)
	v_mfma_f32_32x32x16_bf16 v[48:63], v[120:123], v[84:87], v[48:63]
	v_add_f32_e32 v249, v236, v249
	v_add_f32_e32 v250, v237, v250
	v_add_f32_e32 v249, v228, v249
	v_add_f32_e32 v250, v229, v250
	s_waitcnt lgkmcnt(1)
	v_mfma_f32_32x32x16_bf16 v[64:79], v[112:115], v[88:91], v[64:79]
	v_add_f32_e32 v249, v238, v249
	v_add_f32_e32 v250, v239, v250
	v_add_f32_e32 v249, v230, v249
	v_add_f32_e32 v250, v231, v250
	ds_read_b128 v[112:115], v124 offset:13888
	ds_read_b128 v[252:255], v124 offset:13920
	s_waitcnt lgkmcnt(1)
	v_mfma_f32_32x32x16_bf16 v[48:63], v[112:115], v[88:91], v[48:63]
	v_add_f32_e32 v249, v241, v249
	v_add_f32_e32 v250, v242, v250
	v_add_f32_e32 v249, v232, v249
	v_add_f32_e32 v250, v233, v250
	v_mfma_f32_32x32x16_bf16 v[64:79], v[116:119], v[92:95], v[64:79]
	v_add_f32_e32 v249, v243, v249
	v_add_f32_e32 v250, v244, v250
	v_add_f32_e32 v249, v247, v249
	v_add_f32_e32 v250, v248, v250
	ds_read_b64_tr_b16 v[120:121], v160 offset:30720
	ds_read_b64_tr_b16 v[122:123], v160 offset:32256
	ds_read_b64_tr_b16 v[114:115], v160 offset:32320
	ds_read_b64_tr_b16 v[112:113], v160 offset:30784
	ds_read_b64_tr_b16 v[124:125], v160 offset:33792
	ds_read_b64_tr_b16 v[126:127], v160 offset:35328
	ds_read_b64_tr_b16 v[118:119], v160 offset:35392
	ds_read_b64_tr_b16 v[116:117], v160 offset:33856
	s_waitcnt lgkmcnt(8)
	v_mfma_f32_32x32x16_bf16 v[48:63], v[252:255], v[92:95], v[48:63]
	v_add_f32_e32 v249, v245, v249
	v_add_f32_e32 v250, v246, v250
	v_add_f32_e32 v249, v249, v250
	v_cndmask_b32_e64 v249, 0, v249, s[100:101]
	v_add_f32_e32 v147, v147, v249
	s_mov_b64 s[100:101], 0
	s_cbranch_scc1 .LBB0_933
	v_cmp_le_u32_e64 s[14:15], v161, v149
	v_cmp_le_u32_e64 s[16:17], v162, v149
	v_cmp_le_u32_e64 s[18:19], v164, v149
	v_cmp_le_u32_e64 s[20:21], v166, v149
	v_cmp_le_u32_e64 s[22:23], v168, v149
	v_cmp_le_u32_e64 s[24:25], v170, v149
	v_cmp_le_u32_e64 s[26:27], v172, v149
	v_cmp_le_u32_e64 s[28:29], v174, v149
	v_cmp_le_u32_e64 s[30:31], v176, v149
	v_cmp_le_u32_e64 s[34:35], v178, v149
	v_cmp_le_u32_e64 s[36:37], v180, v149
	v_cmp_le_u32_e64 s[38:39], v182, v149
	v_cmp_le_u32_e64 s[40:41], v184, v149
	v_cmp_le_u32_e64 s[42:43], v186, v149
	v_cmp_le_u32_e64 s[44:45], v189, v149
	s_and_b64 s[14:15], s[4:5], s[14:15]
	s_and_b64 s[16:17], s[4:5], s[16:17]
	s_and_b64 s[18:19], s[4:5], s[18:19]
	s_and_b64 s[20:21], s[4:5], s[20:21]
	s_and_b64 s[22:23], s[4:5], s[22:23]
	s_and_b64 s[24:25], s[4:5], s[24:25]
	s_and_b64 s[26:27], s[4:5], s[26:27]
	s_and_b64 s[28:29], s[4:5], s[28:29]
	s_and_b64 s[30:31], s[4:5], s[30:31]
	s_and_b64 s[34:35], s[4:5], s[34:35]
	s_and_b64 s[36:37], s[4:5], s[36:37]
	s_and_b64 s[38:39], s[4:5], s[38:39]
	s_and_b64 s[40:41], s[4:5], s[40:41]
	s_and_b64 s[42:43], s[4:5], s[42:43]
	s_and_b64 s[44:45], s[4:5], s[44:45]
	v_cmp_gt_u32_e64 s[46:47], v191, v149
	v_cmp_le_u32_e32 vcc, v138, v149
	v_cndmask_b32_e64 v48, v210, v48, s[14:15]
	v_cmp_lt_u32_e64 s[14:15], v138, v149
	v_cndmask_b32_e64 v49, v210, v49, s[16:17]
	v_cmp_le_u32_e64 s[16:17], v163, v149
	v_cndmask_b32_e64 v50, v210, v50, s[18:19]
	v_cmp_le_u32_e64 s[18:19], v165, v149
	v_cndmask_b32_e64 v51, v210, v51, s[20:21]
	v_cmp_le_u32_e64 s[20:21], v167, v149
	v_cndmask_b32_e64 v52, v210, v52, s[22:23]
	v_cmp_le_u32_e64 s[22:23], v169, v149
	v_cndmask_b32_e64 v53, v210, v53, s[24:25]
	v_cmp_le_u32_e64 s[24:25], v171, v149
	v_cndmask_b32_e64 v54, v210, v54, s[26:27]
	v_cmp_le_u32_e64 s[26:27], v173, v149
	v_cndmask_b32_e64 v55, v210, v55, s[28:29]
	v_cmp_le_u32_e64 s[28:29], v175, v149
	v_cndmask_b32_e64 v56, v210, v56, s[30:31]
	v_cmp_le_u32_e64 s[30:31], v177, v149
	v_cndmask_b32_e64 v57, v210, v57, s[34:35]
	v_cmp_le_u32_e64 s[34:35], v179, v149
	v_cndmask_b32_e64 v58, v210, v58, s[36:37]
	v_cmp_le_u32_e64 s[36:37], v181, v149
	v_cndmask_b32_e64 v59, v210, v59, s[38:39]
	v_cmp_le_u32_e64 s[38:39], v183, v149
	v_cndmask_b32_e64 v60, v210, v60, s[40:41]
	v_cmp_le_u32_e64 s[40:41], v185, v149
	v_cndmask_b32_e64 v61, v210, v61, s[42:43]
	v_cmp_le_u32_e64 s[42:43], v187, v149
	v_cndmask_b32_e64 v62, v210, v62, s[44:45]
	v_cmp_le_u32_e64 s[44:45], v190, v149
	s_or_b64 s[50:51], s[50:51], s[46:47]
	s_and_saveexec_b64 s[46:47], s[50:51]
	v_mov_b32_e32 v63, s33
	s_or_b64 exec, exec, s[46:47]
	s_and_b64 vcc, s[4:5], vcc
	v_cndmask_b32_e32 v64, v210, v64, vcc
	s_and_b64 vcc, s[4:5], s[14:15]
	v_cndmask_b32_e32 v65, v210, v65, vcc
	s_and_b64 vcc, s[4:5], s[16:17]
	v_cndmask_b32_e32 v66, v210, v66, vcc
	s_and_b64 vcc, s[4:5], s[18:19]
	v_cndmask_b32_e32 v67, v210, v67, vcc
	s_and_b64 vcc, s[4:5], s[20:21]
	v_cndmask_b32_e32 v68, v210, v68, vcc
	s_and_b64 vcc, s[4:5], s[22:23]
	v_cndmask_b32_e32 v69, v210, v69, vcc
	s_and_b64 vcc, s[4:5], s[24:25]
	v_cndmask_b32_e32 v70, v210, v70, vcc
	s_and_b64 vcc, s[4:5], s[26:27]
	v_cndmask_b32_e32 v71, v210, v71, vcc
	s_and_b64 vcc, s[4:5], s[28:29]
	v_cndmask_b32_e32 v72, v210, v72, vcc
	s_and_b64 vcc, s[4:5], s[30:31]
	v_cndmask_b32_e32 v73, v210, v73, vcc
	s_and_b64 vcc, s[4:5], s[34:35]
	v_cndmask_b32_e32 v74, v210, v74, vcc
	s_and_b64 vcc, s[4:5], s[36:37]
	v_cndmask_b32_e32 v75, v210, v75, vcc
	s_and_b64 vcc, s[4:5], s[38:39]
	v_cndmask_b32_e32 v76, v210, v76, vcc
	s_and_b64 vcc, s[4:5], s[40:41]
	v_cndmask_b32_e32 v77, v210, v77, vcc
	s_and_b64 vcc, s[4:5], s[42:43]
	v_cndmask_b32_e32 v78, v210, v78, vcc
	s_and_b64 vcc, s[4:5], s[44:45]
	v_cndmask_b32_e32 v79, v210, v79, vcc

.LBB0_935:
	v_exp_f32_e32 v215, v64
	v_exp_f32_e32 v214, v48
	v_exp_f32_e32 v217, v65
	v_exp_f32_e32 v216, v49
	v_exp_f32_e32 v219, v66
	v_exp_f32_e32 v218, v50
	v_exp_f32_e32 v221, v67
	v_exp_f32_e32 v225, v68
	v_exp_f32_e32 v235, v69
	v_exp_f32_e32 v227, v70
	v_exp_f32_e32 v237, v71
	v_exp_f32_e32 v220, v51
	v_cvt_pk_bf16_f32 v50, v225, v235
	v_cvt_pk_bf16_f32 v48, v215, v217
	v_cvt_pk_bf16_f32 v49, v219, v221
	v_cvt_pk_bf16_f32 v51, v227, v237
	v_exp_f32_e32 v229, v72
	v_exp_f32_e32 v239, v73
	s_waitcnt lgkmcnt(6)
	v_mfma_f32_32x32x16_bf16 v[0:15], v[120:123], v[48:51], v[0:15]
	v_exp_f32_e32 v231, v74
	v_exp_f32_e32 v242, v75
	v_exp_f32_e32 v233, v76
	v_exp_f32_e32 v244, v77
	v_exp_f32_e32 v248, v78
	v_exp_f32_e32 v246, v79
	v_cvt_pk_bf16_f32 v64, v229, v239
	s_waitcnt lgkmcnt(4)
	v_mfma_f32_32x32x16_bf16 v[16:31], v[112:115], v[48:51], v[16:31]
	v_cvt_pk_bf16_f32 v65, v231, v242
	v_cvt_pk_bf16_f32 v66, v233, v244
	v_cvt_pk_bf16_f32 v67, v248, v246
	v_exp_f32_e32 v224, v52
	v_exp_f32_e32 v234, v53
	v_exp_f32_e32 v226, v54
	v_exp_f32_e32 v236, v55
	s_waitcnt lgkmcnt(2)
	v_mfma_f32_32x32x16_bf16 v[0:15], v[124:127], v[64:67], v[0:15]
	ds_read_b64_tr_b16 v[48:49], v160 offset:36864
	ds_read_b64_tr_b16 v[50:51], v160 offset:38400
	v_exp_f32_e32 v228, v56
	v_exp_f32_e32 v238, v57
	v_exp_f32_e32 v230, v58
	v_exp_f32_e32 v241, v59
	ds_read_b64_tr_b16 v[52:53], v160 offset:39936
	ds_read_b64_tr_b16 v[54:55], v160 offset:41472
	ds_read_b64_tr_b16 v[58:59], v160 offset:38464
	ds_read_b64_tr_b16 v[56:57], v160 offset:36928
	v_exp_f32_e32 v232, v60
	s_waitcnt lgkmcnt(6)
	v_mfma_f32_32x32x16_bf16 v[16:31], v[116:119], v[64:67], v[16:31]
	v_cvt_pk_bf16_f32 v64, v214, v216
	v_cvt_pk_bf16_f32 v65, v218, v220
	v_cvt_pk_bf16_f32 v66, v224, v234
	v_cvt_pk_bf16_f32 v67, v226, v236
	v_exp_f32_e32 v243, v61
	v_exp_f32_e32 v247, v62
	v_exp_f32_e32 v245, v63
	s_waitcnt lgkmcnt(4)
	v_mfma_f32_32x32x16_bf16 v[0:15], v[48:51], v[64:67], v[0:15]
	v_cvt_pk_bf16_f32 v60, v228, v238
	v_cvt_pk_bf16_f32 v61, v230, v241
	v_cvt_pk_bf16_f32 v62, v232, v243
	v_cvt_pk_bf16_f32 v63, v247, v245
	ds_read_b64_tr_b16 v[50:51], v160 offset:41536
	ds_read_b64_tr_b16 v[48:49], v160 offset:40000
	s_waitcnt lgkmcnt(2)
	v_mfma_f32_32x32x16_bf16 v[16:31], v[56:59], v[64:67], v[16:31]
	v_mfma_f32_32x32x16_bf16 v[0:15], v[52:55], v[60:63], v[0:15]
	s_waitcnt lgkmcnt(0)
	v_mfma_f32_32x32x16_bf16 v[16:31], v[48:51], v[60:63], v[16:31]
	s_mov_b64 s[100:101], -1

.Lme_fast:
	v_lshrrev_b32_e32 v48, s54, v146
	v_and_b32_e32 v48, 1, v48
	v_cmp_eq_u32_e32 vcc, 1, v48
	s_cbranch_vccz .LBB0_921
	v_add_u32_e32 v124, v159, v132
	s_nop 0
	v_cndmask_b32_e64 v48, v210, 0, vcc
	v_pk_add_f32 v[62:63], v[46:47], v[48:49] op_sel_hi:[1,0]
	v_pk_add_f32 v[60:61], v[44:45], v[48:49] op_sel_hi:[1,0]
	v_pk_add_f32 v[58:59], v[42:43], v[48:49] op_sel_hi:[1,0]
	v_pk_add_f32 v[56:57], v[40:41], v[48:49] op_sel_hi:[1,0]
	v_pk_add_f32 v[54:55], v[38:39], v[48:49] op_sel_hi:[1,0]
	v_pk_add_f32 v[52:53], v[36:37], v[48:49] op_sel_hi:[1,0]
	v_pk_add_f32 v[50:51], v[34:35], v[48:49] op_sel_hi:[1,0]
	v_pk_add_f32 v[48:49], v[32:33], v[48:49] op_sel_hi:[1,0]
	ds_read_b128 v[112:115], v124
	ds_read_b128 v[116:119], v124 offset:32
	s_waitcnt lgkmcnt(1)
	v_mfma_f32_32x32x16_bf16 v[64:79], v[112:115], v[80:83], v[48:63]
	v_add_f32_e32 v249, v216, v214
	v_add_f32_e32 v250, v217, v215
	v_add_f32_e32 v249, v218, v249
	v_add_f32_e32 v250, v219, v250
	ds_read_b128 v[112:115], v124 offset:4608
	ds_read_b128 v[120:123], v124 offset:4640
	s_waitcnt lgkmcnt(1)
	v_mfma_f32_32x32x16_bf16 v[48:63], v[112:115], v[80:83], v[48:63]
	v_add_f32_e32 v249, v220, v249
	v_add_f32_e32 v250, v221, v250
	v_add_f32_e32 v249, v224, v249
	v_add_f32_e32 v250, v225, v250
	v_mfma_f32_32x32x16_bf16 v[64:79], v[116:119], v[84:87], v[64:79]
	v_add_f32_e32 v249, v234, v249
	v_add_f32_e32 v250, v235, v250
	v_add_f32_e32 v249, v226, v249
	v_add_f32_e32 v250, v227, v250
	ds_read_b128 v[112:115], v124 offset:64
	ds_read_b128 v[116:119], v124 offset:96
	s_waitcnt lgkmcnt(2)
	v_mfma_f32_32x32x16_bf16 v[48:63], v[120:123], v[84:87], v[48:63]
	v_add_f32_e32 v249, v236, v249
	v_add_f32_e32 v250, v237, v250
	v_add_f32_e32 v249, v228, v249
	v_add_f32_e32 v250, v229, v250
	s_waitcnt lgkmcnt(1)
	v_mfma_f32_32x32x16_bf16 v[64:79], v[112:115], v[88:91], v[64:79]
	v_add_f32_e32 v249, v238, v249
	v_add_f32_e32 v250, v239, v250
	v_add_f32_e32 v249, v230, v249
	v_add_f32_e32 v250, v231, v250
	ds_read_b128 v[112:115], v124 offset:4672
	ds_read_b128 v[252:255], v124 offset:4704
	s_waitcnt lgkmcnt(1)
	v_mfma_f32_32x32x16_bf16 v[48:63], v[112:115], v[88:91], v[48:63]
	v_add_f32_e32 v249, v241, v249
	v_add_f32_e32 v250, v242, v250
	v_add_f32_e32 v249, v232, v249
	v_add_f32_e32 v250, v233, v250
	v_mfma_f32_32x32x16_bf16 v[64:79], v[116:119], v[92:95], v[64:79]
	v_add_f32_e32 v249, v243, v249
	v_add_f32_e32 v250, v244, v250
	v_add_f32_e32 v249, v247, v249
	v_add_f32_e32 v250, v248, v250
	ds_read_b64_tr_b16 v[120:121], v160 offset:18432
	ds_read_b64_tr_b16 v[122:123], v160 offset:19968
	ds_read_b64_tr_b16 v[114:115], v160 offset:20032
	ds_read_b64_tr_b16 v[112:113], v160 offset:18496
	ds_read_b64_tr_b16 v[124:125], v160 offset:21504
	ds_read_b64_tr_b16 v[126:127], v160 offset:23040
	ds_read_b64_tr_b16 v[118:119], v160 offset:23104
	ds_read_b64_tr_b16 v[116:117], v160 offset:21568
	s_waitcnt lgkmcnt(8)
	v_mfma_f32_32x32x16_bf16 v[48:63], v[252:255], v[92:95], v[48:63]
	v_add_f32_e32 v249, v245, v249
	v_add_f32_e32 v250, v246, v250
	v_add_f32_e32 v249, v249, v250
	v_cndmask_b32_e64 v249, 0, v249, s[100:101]
	v_add_f32_e32 v147, v147, v249
	s_mov_b64 s[100:101], 0
	s_branch .LBB0_918
.Lmo_fast:
	v_lshrrev_b32_e32 v48, s54, v146
	v_and_b32_e32 v48, 1, v48
	v_cmp_eq_u32_e32 vcc, 1, v48
	s_cbranch_vccz .LBB0_936
	v_add_u32_e32 v124, v159, v132
	s_nop 0
	v_cndmask_b32_e64 v48, v210, 0, vcc
	v_pk_add_f32 v[62:63], v[46:47], v[48:49] op_sel_hi:[1,0]
	v_pk_add_f32 v[60:61], v[44:45], v[48:49] op_sel_hi:[1,0]
	v_pk_add_f32 v[58:59], v[42:43], v[48:49] op_sel_hi:[1,0]
	v_pk_add_f32 v[56:57], v[40:41], v[48:49] op_sel_hi:[1,0]
	v_pk_add_f32 v[54:55], v[38:39], v[48:49] op_sel_hi:[1,0]
	v_pk_add_f32 v[52:53], v[36:37], v[48:49] op_sel_hi:[1,0]
	v_pk_add_f32 v[50:51], v[34:35], v[48:49] op_sel_hi:[1,0]
	v_pk_add_f32 v[48:49], v[32:33], v[48:49] op_sel_hi:[1,0]
	ds_read_b128 v[112:115], v124 offset:9216
	ds_read_b128 v[116:119], v124 offset:9248
	s_waitcnt lgkmcnt(1)
	v_mfma_f32_32x32x16_bf16 v[64:79], v[112:115], v[80:83], v[48:63]
	v_add_f32_e32 v249, v216, v214
	v_add_f32_e32 v250, v217, v215
	v_add_f32_e32 v249, v218, v249
	v_add_f32_e32 v250, v219, v250
	ds_read_b128 v[112:115], v124 offset:13824
	ds_read_b128 v[120:123], v124 offset:13856
	s_waitcnt lgkmcnt(1)
	v_mfma_f32_32x32x16_bf16 v[48:63], v[112:115], v[80:83], v[48:63]
	v_add_f32_e32 v249, v220, v249
	v_add_f32_e32 v250, v221, v250
	v_add_f32_e32 v249, v224, v249
	v_add_f32_e32 v250, v225, v250
	v_mfma_f32_32x32x16_bf16 v[64:79], v[116:119], v[84:87], v[64:79]
	v_add_f32_e32 v249, v234, v249
	v_add_f32_e32 v250, v235, v250
	v_add_f32_e32 v249, v226, v249
	v_add_f32_e32 v250, v227, v250
	ds_read_b128 v[112:115], v124 offset:9280
	ds_read_b128 v[116:119], v124 offset:9312
	s_waitcnt lgkmcnt(2)
	v_mfma_f32_32x32x16_bf16 v[48:63], v[120:123], v[84:87], v[48:63]
	v_add_f32_e32 v249, v236, v249
	v_add_f32_e32 v250, v237, v250
	v_add_f32_e32 v249, v228, v249
	v_add_f32_e32 v250, v229, v250
	s_waitcnt lgkmcnt(1)
	v_mfma_f32_32x32x16_bf16 v[64:79], v[112:115], v[88:91], v[64:79]
	v_add_f32_e32 v249, v238, v249
	v_add_f32_e32 v250, v239, v250
	v_add_f32_e32 v249, v230, v249
	v_add_f32_e32 v250, v231, v250
	ds_read_b128 v[112:115], v124 offset:13888
	ds_read_b128 v[252:255], v124 offset:13920
	s_waitcnt lgkmcnt(1)
	v_mfma_f32_32x32x16_bf16 v[48:63], v[112:115], v[88:91], v[48:63]
	v_add_f32_e32 v249, v241, v249
	v_add_f32_e32 v250, v242, v250
	v_add_f32_e32 v249, v232, v249
	v_add_f32_e32 v250, v233, v250
	v_mfma_f32_32x32x16_bf16 v[64:79], v[116:119], v[92:95], v[64:79]
	v_add_f32_e32 v249, v243, v249
	v_add_f32_e32 v250, v244, v250
	v_add_f32_e32 v249, v247, v249
	v_add_f32_e32 v250, v248, v250
	ds_read_b64_tr_b16 v[120:121], v160 offset:30720
	ds_read_b64_tr_b16 v[122:123], v160 offset:32256
	ds_read_b64_tr_b16 v[114:115], v160 offset:32320
	ds_read_b64_tr_b16 v[112:113], v160 offset:30784
	ds_read_b64_tr_b16 v[124:125], v160 offset:33792
	ds_read_b64_tr_b16 v[126:127], v160 offset:35328
	ds_read_b64_tr_b16 v[118:119], v160 offset:35392
	ds_read_b64_tr_b16 v[116:117], v160 offset:33856
	s_waitcnt lgkmcnt(8)
	v_mfma_f32_32x32x16_bf16 v[48:63], v[252:255], v[92:95], v[48:63]
	v_add_f32_e32 v249, v245, v249
	v_add_f32_e32 v250, v246, v250
	v_add_f32_e32 v249, v249, v250
	v_cndmask_b32_e64 v249, 0, v249, s[100:101]
	v_add_f32_e32 v147, v147, v249
	s_mov_b64 s[100:101], 0
	s_branch .LBB0_933
.LBB0_938:
	v_add_f32_e32 v249, v216, v214
	v_add_f32_e32 v250, v217, v215
	v_add_f32_e32 v249, v218, v249
	v_add_f32_e32 v250, v219, v250
	v_add_f32_e32 v249, v220, v249
	v_add_f32_e32 v250, v221, v250
	v_add_f32_e32 v249, v224, v249
	v_add_f32_e32 v250, v225, v250
	v_add_f32_e32 v249, v234, v249
	v_add_f32_e32 v250, v235, v250
	v_add_f32_e32 v249, v226, v249
	v_add_f32_e32 v250, v227, v250
	v_add_f32_e32 v249, v236, v249
	v_add_f32_e32 v250, v237, v250
	v_add_f32_e32 v249, v228, v249
	v_add_f32_e32 v250, v229, v250
	v_add_f32_e32 v249, v238, v249
	v_add_f32_e32 v250, v239, v250
	v_add_f32_e32 v249, v230, v249
	v_add_f32_e32 v250, v231, v250
	v_add_f32_e32 v249, v241, v249
	v_add_f32_e32 v250, v242, v250
	v_add_f32_e32 v249, v232, v249
	v_add_f32_e32 v250, v233, v250
	v_add_f32_e32 v249, v243, v249
	v_add_f32_e32 v250, v244, v250
	v_add_f32_e32 v249, v247, v249
	v_add_f32_e32 v250, v248, v250
	v_add_f32_e32 v249, v245, v249
	v_add_f32_e32 v250, v246, v250
	v_add_f32_e32 v249, v249, v250
	v_cndmask_b32_e64 v249, 0, v249, s[100:101]
	v_add_f32_e32 v147, v147, v249
	s_mov_b64 s[100:101], 0
	v_mov_b32_e32 v32, v147
	v_mov_b32_e32 v33, v147
	s_nop 1
	v_permlane32_swap_b32_e32 v32, v33
	v_cndmask_b32_e64 v32, v32, v33, s[6:7]
	v_add_f32_e32 v32, v147, v32
	v_div_scale_f32 v33, s[4:5], v32, v32, 1.0
	v_rcp_f32_e32 v34, v33
	s_ashr_i32 s2, s0, 3
	s_ashr_i32 s3, s2, 31
	s_lshl_b64 s[2:3], s[2:3], 21
	v_fma_f32 v35, -v33, v34, 1.0
	v_fmac_f32_e32 v34, v35, v34
	v_div_scale_f32 v35, vcc, 1.0, v32, 1.0
	v_mul_f32_e32 v36, v35, v34
	v_fma_f32 v37, -v33, v36, v35
	v_fmac_f32_e32 v36, v37, v34
	v_fma_f32 v33, -v33, v36, v35
	v_div_fmas_f32 v33, v33, v34, v36
	v_div_fixup_f32 v33, v33, v32, 1.0
	v_cmp_lt_f32_e32 vcc, 0, v32
	v_readlane_b32 s1, v240, 36
	s_add_u32 s2, s1, s2
	v_cndmask_b32_e32 v34, 0, v33, vcc
	v_readlane_b32 s1, v240, 37
	v_pk_mul_f32 v[32:33], v[0:1], v[34:35] op_sel_hi:[1,0]
	v_pk_mul_f32 v[0:1], v[16:17], v[34:35] op_sel_hi:[1,0]
	v_pk_mul_f32 v[16:17], v[2:3], v[34:35] op_sel_hi:[1,0]
	v_pk_mul_f32 v[2:3], v[18:19], v[34:35] op_sel_hi:[1,0]
	v_pk_mul_f32 v[18:19], v[4:5], v[34:35] op_sel_hi:[1,0]
	v_pk_mul_f32 v[4:5], v[20:21], v[34:35] op_sel_hi:[1,0]
	v_pk_mul_f32 v[20:21], v[6:7], v[34:35] op_sel_hi:[1,0]
	v_pk_mul_f32 v[6:7], v[22:23], v[34:35] op_sel_hi:[1,0]
	v_pk_mul_f32 v[22:23], v[8:9], v[34:35] op_sel_hi:[1,0]
	v_pk_mul_f32 v[8:9], v[24:25], v[34:35] op_sel_hi:[1,0]
	v_pk_mul_f32 v[24:25], v[10:11], v[34:35] op_sel_hi:[1,0]
	v_pk_mul_f32 v[10:11], v[26:27], v[34:35] op_sel_hi:[1,0]
	v_pk_mul_f32 v[26:27], v[12:13], v[34:35] op_sel_hi:[1,0]
	v_pk_mul_f32 v[12:13], v[28:29], v[34:35] op_sel_hi:[1,0]
	v_pk_mul_f32 v[28:29], v[14:15], v[34:35] op_sel_hi:[1,0]
	v_pk_mul_f32 v[14:15], v[30:31], v[34:35] op_sel_hi:[1,0]
	s_addc_u32 s3, s1, s3
	v_lshlrev_b64 v[30:31], 10, v[128:129]
	s_lshl_b32 s1, s0, 6
	v_lshl_add_u64 v[30:31], s[2:3], 0, v[30:31]
	s_and_b32 s96, s1, 0x1c0
	s_waitcnt lgkmcnt(0)
	s_barrier
	s_branch .LBB0_870
